# v3 + acquire (buffer_inv sc1) issued by wave 1 in parallel with thread 0 atomic chain, all 12 seams
# speedup vs baseline: 1.0107x; 1.0097x over previous
.LBB0_180:
	s_or_b64 exec, exec, s[14:15]
	s_waitcnt vmcnt(0)
	s_branch .LBB0_181
.Lseam0_aux:
	s_or_b64 exec, exec, s[8:9]
	v_readfirstlane_b32 s98, v213
	s_nop 3
	s_lshr_b32 s98, s98, 6
	s_cmp_lg_u32 s98, 1
	s_cbranch_scc1 .LBB0_181
	buffer_inv sc1
	s_waitcnt vmcnt(0)

.LBB0_388:
	s_andn2_saveexec_b64 s[12:13], s[12:13]
	s_cbranch_execz .LBB0_408
	s_mov_b64 s[12:13], exec
	s_waitcnt lgkmcnt(0)
	s_waitcnt vmcnt(0)
	v_mbcnt_lo_u32_b32 v1, s12, 0
	v_mbcnt_hi_u32_b32 v1, s13, v1
	v_cmp_eq_u32_e32 vcc, 0, v1
	s_and_saveexec_b64 s[14:15], vcc
	s_cbranch_execz .LBB0_391
	s_bcnt1_i32_b64 s3, s[12:13]
	v_mov_b32_e32 v2, 0x3000
	v_mov_b32_e32 v3, s3
	global_atomic_add v2, v2, v3, s[42:43] offset:1280 sc0

.Lseam3_aux:
	s_or_b64 exec, exec, s[6:7]
	v_readfirstlane_b32 s98, v213
	s_nop 3
	s_lshr_b32 s98, s98, 6
	s_cmp_lg_u32 s98, 1
	s_cbranch_scc1 .LBB0_604
	buffer_inv sc1
	s_waitcnt vmcnt(0)

.LBB0_1467:
	s_andn2_saveexec_b64 s[10:11], s[10:11]
	s_cbranch_execz .LBB0_1487
	s_mov_b64 s[10:11], exec
	s_waitcnt lgkmcnt(0)
	s_waitcnt vmcnt(0)
	v_mbcnt_lo_u32_b32 v1, s10, 0
	v_mbcnt_hi_u32_b32 v1, s11, v1
	v_cmp_eq_u32_e32 vcc, 0, v1
	s_and_saveexec_b64 s[12:13], vcc
	s_cbranch_execz .LBB0_1470
	s_bcnt1_i32_b64 s3, s[10:11]
	v_mov_b32_e32 v2, 0x3000
	v_mov_b32_e32 v3, s3
	global_atomic_add v2, v2, v3, s[42:43] offset:1280 sc0

.LBB0_1486:
	s_or_b64 exec, exec, s[12:13]
	s_waitcnt vmcnt(0)
	s_branch .LBB0_1487

	.amdhsa_kernel _Z8yoco_fwd4Args
		.amdhsa_group_segment_fixed_size 0
		.amdhsa_private_segment_fixed_size 0
		.amdhsa_kernarg_size 480
		.amdhsa_user_sgpr_count 2
		.amdhsa_user_sgpr_dispatch_ptr 0
		.amdhsa_user_sgpr_queue_ptr 0
		.amdhsa_user_sgpr_kernarg_segment_ptr 1
		.amdhsa_user_sgpr_dispatch_id 0
		.amdhsa_user_sgpr_kernarg_preload_length 0
		.amdhsa_user_sgpr_kernarg_preload_offset 0
		.amdhsa_user_sgpr_private_segment_size 0
		.amdhsa_uses_dynamic_stack 0
		.amdhsa_enable_private_segment 0
		.amdhsa_system_sgpr_workgroup_id_x 1
		.amdhsa_system_sgpr_workgroup_id_y 0
		.amdhsa_system_sgpr_workgroup_id_z 0
		.amdhsa_system_sgpr_workgroup_info 0
		.amdhsa_system_vgpr_workitem_id 2
		.amdhsa_next_free_vgpr 253
		.amdhsa_next_free_sgpr 100
		.amdhsa_accum_offset 256
		.amdhsa_reserve_vcc 1
		.amdhsa_float_round_mode_32 0
		.amdhsa_float_round_mode_16_64 0
		.amdhsa_float_denorm_mode_32 3
		.amdhsa_float_denorm_mode_16_64 3
		.amdhsa_dx10_clamp 1
		.amdhsa_ieee_mode 1
		.amdhsa_fp16_overflow 0
		.amdhsa_tg_split 0
		.amdhsa_exception_fp_ieee_invalid_op 0
		.amdhsa_exception_fp_denorm_src 0
		.amdhsa_exception_fp_ieee_div_zero 0
		.amdhsa_exception_fp_ieee_overflow 0
		.amdhsa_exception_fp_ieee_underflow 0
		.amdhsa_exception_fp_ieee_inexact 0
		.amdhsa_exception_int_div_zero 0
	.end_amdhsa_kernel

amdhsa.kernels:
  - .agpr_count:     0
    .args:
      - .offset:         0
        .size:           224
        .value_kind:     by_value
      - .offset:         224
        .size:           4
        .value_kind:     hidden_block_count_x
      - .offset:         228
        .size:           4
        .value_kind:     hidden_block_count_y
      - .offset:         232
        .size:           4
        .value_kind:     hidden_block_count_z
      - .offset:         236
        .size:           2
        .value_kind:     hidden_group_size_x
      - .offset:         238
        .size:           2
        .value_kind:     hidden_group_size_y
      - .offset:         240
        .size:           2
        .value_kind:     hidden_group_size_z
      - .offset:         242
        .size:           2
        .value_kind:     hidden_remainder_x
      - .offset:         244
        .size:           2
        .value_kind:     hidden_remainder_y
      - .offset:         246
        .size:           2
        .value_kind:     hidden_remainder_z
      - .offset:         264
        .size:           8
        .value_kind:     hidden_global_offset_x
      - .offset:         272
        .size:           8
        .value_kind:     hidden_global_offset_y
      - .offset:         280
        .size:           8
        .value_kind:     hidden_global_offset_z
      - .offset:         288
        .size:           2
        .value_kind:     hidden_grid_dims
      - .offset:         312
        .size:           8
        .value_kind:     hidden_multigrid_sync_arg
      - .offset:         344
        .size:           4
        .value_kind:     hidden_dynamic_lds_size
    .group_segment_fixed_size: 0
    .kernarg_segment_align: 8
    .kernarg_segment_size: 480
    .language:       OpenCL C
    .language_version:
      - 2
      - 0
    .max_flat_workgroup_size: 512
    .name:           _Z8yoco_fwd4Args
    .private_segment_fixed_size: 0
    .sgpr_count:     106
    .sgpr_spill_count: 10
    .symbol:         _Z8yoco_fwd4Args.kd
    .uniform_work_group_size: 1
    .uses_dynamic_stack: false
    .vgpr_count:     253
    .vgpr_spill_count: 0
    .wavefront_size: 64
